# skip the grid barrier after the very last phase (layer 1 N3) - kernel ends there
# speedup vs baseline: 1.0140x; 1.0057x over previous
; __global__ void __launch_bounds__(512, 2) fwd_megakernel(Params P) {
;     ...
;         xcd_barrier(xbar, wv);
;         { PH_IDS phase_norm_out(P, l, gw, NGW, lane);
;           if (l == 0) { __syncthreads(); convert_mixer_weights(P, 1, lds, gw, NGW, wave, lane, false); } }
;         xcd_barrier(xbar, wv);
;     }
; }
.LBB0_2166:
	s_endpgm
.Lfinal_exit:
	s_endpgm
